# s5_gen Kt loop hand-scheduled with scalar fmac (no packed-math shuffles), s5_gen 35 to 26 us
# speedup vs baseline: 1.0110x; 1.0051x over previous
; __device__ __forceinline__ void s5_gen(LAS unsigned char* lds, int g, int part, int tid, const float* lam_re, const float* lam_im, const float* log_step, const float* b_re, const float* b_im, ...
;     ...
;     { const int dir = tid >> 8, h = (tid >> 4) & 15, h2 = tid & 15; float acc[16];
; #pragma unroll
;       for (int j = 0; j < 16; ++j) acc[j] = 0.f;
;       for (int p = 0; p < 64; ++p) { const cplx cc{Cc[((dir * 16 + h) * 64 + p) * 2], Cc[((dir * 16 + h) * 64 + p) * 2 + 1]}, bb{Bb[((dir * 64 + p) * 16 + h2) * 2], Bb[((dir * 64 + p) * 16 + h2) * 2 + 1]};
;           const cplx cb = cmul(cc, bb);
; #pragma unroll
;           for (int j = 0; j < 16; ++j) { const float lr = L[((dir * 17 + j) * 64 + p) * 2], li = L[((dir * 17 + j) * 64 + p) * 2 + 1]; acc[j] += cb.re * lr - cb.im * li; } }
; #pragma unroll
;       for (int j = 0; j < 16; ++j) Kt[(dir * 16 + j) * 256 + h * 16 + h2] = acc[j]; }
;     __syncthreads();
;     for (int e = tid; e < 64 * 256; e += 512) { const int n = 64 * part + (e >> 8), kp = e & 255, tl = n >> 4, h = n & 15; float v[2];
.LBB0_568:
	ds_read2_b64 v[2:5], v26 offset1:16
	v_add_u32_e32 v27, s0, v25
	v_add_u32_e32 v96, s0, v24
	ds_read_b128 v[28:31], v27
	ds_read_b128 v[32:35], v96
	ds_read_b128 v[36:39], v96 offset:512
	ds_read_b128 v[40:43], v96 offset:1024
	ds_read_b128 v[44:47], v96 offset:1536
	ds_read_b128 v[48:51], v96 offset:2048
	ds_read_b128 v[52:55], v96 offset:2560
	ds_read_b128 v[56:59], v96 offset:3072
	ds_read_b128 v[60:63], v96 offset:3584
	ds_read_b128 v[64:67], v96 offset:4096
	ds_read_b128 v[68:71], v96 offset:4608
	ds_read_b128 v[72:75], v96 offset:5120
	ds_read_b128 v[76:79], v96 offset:5632
	ds_read_b128 v[80:83], v96 offset:6144
	ds_read_b128 v[84:87], v96 offset:6656
	ds_read_b128 v[88:91], v96 offset:7168
	ds_read_b128 v[92:95], v96 offset:7680
	v_add_u32_e32 v26, 0x100, v26
	s_add_i32 s0, s0, 16
	s_waitcnt lgkmcnt(15)
	v_mul_f32_e32 v97, v28, v2
	v_mul_f32_e64 v98, -v28, v3
	v_mul_f32_e32 v99, v30, v4
	v_mul_f32_e64 v100, -v30, v5
	v_fma_f32 v97, -v29, v3, v97
	v_fma_f32 v98, -v29, v2, v98
	v_fma_f32 v99, -v31, v5, v99
	v_fma_f32 v100, -v31, v4, v100
	s_waitcnt lgkmcnt(12)
	v_fmac_f32_e32 v10, v97, v32
	v_fmac_f32_e32 v11, v97, v36
	v_fmac_f32_e32 v12, v97, v40
	v_fmac_f32_e32 v13, v97, v44
	s_waitcnt lgkmcnt(8)
	v_fmac_f32_e32 v14, v97, v48
	v_fmac_f32_e32 v15, v97, v52
	v_fmac_f32_e32 v16, v97, v56
	v_fmac_f32_e32 v17, v97, v60
	s_waitcnt lgkmcnt(4)
	v_fmac_f32_e32 v18, v97, v64
	v_fmac_f32_e32 v19, v97, v68
	v_fmac_f32_e32 v20, v97, v72
	v_fmac_f32_e32 v21, v97, v76
	s_waitcnt lgkmcnt(0)
	v_fmac_f32_e32 v22, v97, v80
	v_fmac_f32_e32 v23, v97, v84
	v_fmac_f32_e32 v8, v97, v88
	v_fmac_f32_e32 v9, v97, v92
	v_fmac_f32_e32 v10, v98, v33
	v_fmac_f32_e32 v11, v98, v37
	v_fmac_f32_e32 v12, v98, v41
	v_fmac_f32_e32 v13, v98, v45
	v_fmac_f32_e32 v14, v98, v49
	v_fmac_f32_e32 v15, v98, v53
	v_fmac_f32_e32 v16, v98, v57
	v_fmac_f32_e32 v17, v98, v61
	v_fmac_f32_e32 v18, v98, v65
	v_fmac_f32_e32 v19, v98, v69
	v_fmac_f32_e32 v20, v98, v73
	v_fmac_f32_e32 v21, v98, v77
	v_fmac_f32_e32 v22, v98, v81
	v_fmac_f32_e32 v23, v98, v85
	v_fmac_f32_e32 v8, v98, v89
	v_fmac_f32_e32 v9, v98, v93
	v_fmac_f32_e32 v10, v99, v34
	v_fmac_f32_e32 v11, v99, v38
	v_fmac_f32_e32 v12, v99, v42
	v_fmac_f32_e32 v13, v99, v46
	v_fmac_f32_e32 v14, v99, v50
	v_fmac_f32_e32 v15, v99, v54
	v_fmac_f32_e32 v16, v99, v58
	v_fmac_f32_e32 v17, v99, v62
	v_fmac_f32_e32 v18, v99, v66
	v_fmac_f32_e32 v19, v99, v70
	v_fmac_f32_e32 v20, v99, v74
	v_fmac_f32_e32 v21, v99, v78
	v_fmac_f32_e32 v22, v99, v82
	v_fmac_f32_e32 v23, v99, v86
	v_fmac_f32_e32 v8, v99, v90
	v_fmac_f32_e32 v9, v99, v94
	v_fmac_f32_e32 v10, v100, v35
	v_fmac_f32_e32 v11, v100, v39
	v_fmac_f32_e32 v12, v100, v43
	v_fmac_f32_e32 v13, v100, v47
	v_fmac_f32_e32 v14, v100, v51
	v_fmac_f32_e32 v15, v100, v55
	v_fmac_f32_e32 v16, v100, v59
	v_fmac_f32_e32 v17, v100, v63
	v_fmac_f32_e32 v18, v100, v67
	v_fmac_f32_e32 v19, v100, v71
	v_fmac_f32_e32 v20, v100, v75
	v_fmac_f32_e32 v21, v100, v79
	v_fmac_f32_e32 v22, v100, v83
	v_fmac_f32_e32 v23, v100, v87
	v_fmac_f32_e32 v8, v100, v91
	v_fmac_f32_e32 v9, v100, v95
	s_cmpk_eq_i32 s0, 0x200
	s_cbranch_scc0 .LBB0_568
	v_lshlrev_b32_e32 v2, 2, v6
	v_and_b32_e32 v2, 0x3c0, v2
	v_lshl_add_u32 v1, v1, 14, 0
	v_lshlrev_b32_e32 v3, 2, v7
	s_movk_i32 s0, 0x4000
	s_and_b32 s21, s88, 3
	s_mov_b32 s9, 0
	v_add3_u32 v1, v1, v2, v3
	v_cmp_gt_i32_e32 vcc, s0, v6
	v_add_u32_e32 v2, 0xc400, v1
	ds_write2st64_b32 v1, v10, v11 offset0:196 offset1:200
	ds_write2st64_b32 v1, v12, v13 offset0:204 offset1:208
	ds_write2st64_b32 v1, v14, v15 offset0:212 offset1:216
	ds_write2st64_b32 v1, v16, v17 offset0:220 offset1:224
	ds_write2st64_b32 v1, v18, v19 offset0:228 offset1:232
	ds_write2st64_b32 v1, v20, v21 offset0:236 offset1:240
	ds_write2st64_b32 v1, v22, v23 offset0:244 offset1:248
	ds_write_b32 v1, v8 offset:64512
	ds_write_b32 v2, v9 offset:15360
	s_waitcnt lgkmcnt(0)
	s_barrier
	s_and_saveexec_b64 s[10:11], vcc
	s_cbranch_execz .LBB0_592
	v_mov_b32_e32 v1, 1
	v_lshlrev_b32_sdwa v1, v1, v6 dst_sel:DWORD dst_unused:UNUSED_PAD src0_sel:DWORD src1_sel:BYTE_0
	v_add_u32_e32 v2, 0xffffff00, v1
	s_movk_i32 s0, 0x80
	v_lshrrev_b32_e32 v3, 7, v2
	v_cmp_gt_u32_e32 vcc, s0, v2
	v_mov_b32_e32 v2, 2
	v_lshlrev_b32_e32 v7, 10, v3
	v_lshl_add_u32 v12, v3, 4, v3
	s_movk_i32 s0, 0x7f
	v_and_b32_e32 v14, 62, v1
	v_bitop3_b32 v18, v1, 63, 1 bitop3:0xc8
	v_lshlrev_b32_sdwa v2, v2, v6 dst_sel:DWORD dst_unused:UNUSED_PAD src0_sel:DWORD src1_sel:BYTE_0
	v_mov_b32_e32 v3, 0
	s_lshl_b32 s22, s21, 6
	s_lshl_b32 s23, s20, 4
	s_lshl_b32 s8, s20, 8
	v_bfe_u32 v13, v6, 3, 5
	v_cmp_gt_u32_sdwa s[12:13], v6, s0 src0_sel:BYTE_0 src1_sel:DWORD
	v_lshlrev_b32_e32 v15, 3, v14
	v_and_b32_e32 v16, 14, v1
	v_or_b32_e32 v17, 1, v1
	v_lshlrev_b32_e32 v19, 3, v18
	v_bitop3_b32 v20, v1, 15, 1 bitop3:0xc8
	v_lshl_add_u64 v[4:5], s[82:83], 0, v[2:3]
	s_mov_b64 s[14:15], 0
	s_movk_i32 s24, 0x7fff
	v_mov_b32_e32 v21, v6
	s_branch .LBB0_573
